# tile placement S: 840 FFN2 gate/up conversion tiles moved from the P9 idle WGs to the P1 tail (WGs>=172), P9 keeps 368
# baseline (speedup 1.0000x reference)
; __device__ __forceinline__ int fresh_tid(int wv) { int l; asm volatile("v_mbcnt_lo_u32_b32 %0, -1, 0\n\tv_mbcnt_hi_u32_b32 %0, -1, %0" : "=v"(l)); return wv * 64 + l; }
; #define LAS __attribute__((address_space(3)))
; #define PH(k) if ((PHM >> (k)) & 1)
; __device__ __forceinline__ void tconv_list(const float* wg, const float* wu, const float* wd, const float* win, const float* wout, unsigned char* ws, const int ntiles, LAS float* t, const int wv) {
;     const int tid = fresh_tid(wv); const int G = gridDim.x;
;     float cur[8], nxt[8];
;     int i = blockIdx.x;
;     if (i < ntiles) { const TDesc d = tconv_desc(wg, wu, wd, win, wout, ws, i);
; #pragma unroll
;         for (int e = 0; e < 8; ++e) { const int idx = e * 512 + tid, r = idx >> 6, c = idx & 63; cur[e] = __builtin_nontemporal_load(d.W + (size_t)(d.k0 + r) * d.N + d.n0 + c); } }
; __global__ void __launch_bounds__(512, 2) hymba_mega(Params P_unused) {
;     ...
;     PH(1) { pg8::Gemm g{XN, (const bf16_t*)(ws + WS_WGU), MT, NGU, 1024}; S.init(MT, NGU, G, bx, 1024); pg8::EpiSwiGLU E{ACT, DFF}; pg8::gemm_phase(lds, g, S, E, wv); }
.Ltc1_skip:
	s_cmp_lt_u32 s2, 172
	s_cbranch_scc1 .Ltc6_skip
	v_writelane_b32 v40, s4, 4
	v_writelane_b32 v40, s5, 5
	v_writelane_b32 v40, s6, 6
	v_writelane_b32 v40, s7, 7
	v_writelane_b32 v40, s8, 8
	v_writelane_b32 v40, s9, 9
	v_writelane_b32 v40, s10, 10
	v_writelane_b32 v40, s11, 11
	v_writelane_b32 v40, s12, 12
	v_writelane_b32 v40, s13, 13
	v_writelane_b32 v40, s14, 14
	v_writelane_b32 v40, s15, 15
	v_writelane_b32 v40, s16, 16
	v_writelane_b32 v40, s17, 17
	v_writelane_b32 v40, s18, 18
	v_writelane_b32 v40, s19, 19
	v_writelane_b32 v40, s20, 20
	v_writelane_b32 v40, s21, 21
	v_writelane_b32 v40, s22, 22
	v_writelane_b32 v40, s23, 23
	v_writelane_b32 v40, s24, 24
	v_writelane_b32 v40, s25, 25
	v_writelane_b32 v40, s26, 26
	v_writelane_b32 v40, s27, 27
	v_writelane_b32 v40, s28, 28
	v_writelane_b32 v40, s29, 29
	v_writelane_b32 v40, s30, 30
	v_writelane_b32 v40, s31, 31
	s_load_dwordx2 s[24:25], s[0:1], 0xd8
	s_load_dwordx2 s[26:27], s[0:1], 0xd0
	s_load_dwordx2 s[18:19], s[0:1], 0xb8
	s_load_dwordx2 s[20:21], s[0:1], 0xc0
	s_load_dwordx2 s[22:23], s[0:1], 0xc8
	v_mbcnt_lo_u32_b32 v0, -1, 0
	v_mbcnt_hi_u32_b32 v0, -1, v0
	s_lshr_b32 s28, s33, 6
	v_lshlrev_b32_e32 v1, 2, v0
	v_lshrrev_b32_e32 v2, 5, v0
	v_and_b32_e32 v3, 31, v0
	s_mul_i32 s7, s28, 260
	v_add_u32_e32 v5, s7, v1
	v_mul_u32_u24_e32 v6, 0x208, v3
	s_lshl_b32 s7, s28, 3
	v_lshl_add_u32 v6, v2, 2, v6
	v_add_u32_e32 v6, s7, v6
	v_lshlrev_b32_e32 v3, 2, v3
	s_sub_u32 s4, s2, 172
	s_waitcnt lgkmcnt(0)
	s_cmp_lt_u32 s4, 704
	s_cbranch_scc0 .Ltc6_seg1_0
	s_mov_b32 s7, s4
	s_and_b32 s8, s7, 15
	s_lshr_b32 s9, s7, 4
	s_mul_i32 s7, s8, 720896
	s_lshl_b32 s29, s9, 8
	s_add_u32 s7, s7, s29
	s_mul_i32 s29, s28, 11264
	s_add_u32 s7, s7, s29
	s_add_u32 s10, s18, s7
	s_addc_u32 s11, s19, 0
	s_lshr_b32 s7, s9, 1
	s_lshl_b32 s7, s7, 8
	s_and_b32 s29, s9, 1
	s_lshl_b32 s29, s29, 6
	s_add_u32 s7, s7, s29
	s_mul_i32 s7, s7, 2048
	s_lshl_b32 s29, s8, 7
	s_add_u32 s7, s7, s29
	s_mul_i32 s29, s28, 4096
	s_add_u32 s7, s7, s29
	s_add_u32 s12, s26, 0x2100000
	s_addc_u32 s13, s27, 0
	s_add_u32 s12, s12, s7
	s_addc_u32 s13, s13, 0
	s_mov_b32 s14, 90112
	s_mov_b32 s15, 32768
	s_movk_i32 s16, 2048
	s_branch .Ltc6_segend_0

; __device__ __forceinline__ void tconv_list(const float* wg, const float* wu, const float* wd, const float* win, const float* wout, unsigned char* ws, const int ntiles, LAS float* t, const int wv) {
;     ...
;     for (; i < ntiles; i += G) {
;         const TDesc d = tconv_desc(wg, wu, wd, win, wout, ws, i);
;         { const TDesc dn = tconv_desc(wg, wu, wd, win, wout, ws, i + G < ntiles ? i + G : i);
; #pragma unroll
;             for (int e = 0; e < 8; ++e) { const int idx = e * 512 + tid, r = idx >> 6, c = idx & 63; nxt[e] = __builtin_nontemporal_load(dn.W + (size_t)(dn.k0 + r) * dn.N + dn.n0 + c); } }
.Ltc6_loop:
	s_add_u32 s4, s4, 84
	s_cmp_lt_u32 s4, 840
	s_cselect_b32 s31, 1, 0
	s_cbranch_scc0 .Ltc6_nonexta
	v_writelane_b32 v40, s8, 32
	v_writelane_b32 v40, s9, 33
	s_cmp_lt_u32 s4, 704
	s_cbranch_scc0 .Ltc6_seg1_1
	s_mov_b32 s7, s4
	s_and_b32 s8, s7, 15
	s_lshr_b32 s9, s7, 4
	s_mul_i32 s7, s8, 720896
	s_lshl_b32 s29, s9, 8
	s_add_u32 s7, s7, s29
	s_mul_i32 s29, s28, 11264
	s_add_u32 s7, s7, s29
	s_add_u32 s10, s18, s7
	s_addc_u32 s11, s19, 0
	s_lshr_b32 s7, s9, 1
	s_lshl_b32 s7, s7, 8
	s_and_b32 s29, s9, 1
	s_lshl_b32 s29, s29, 6
	s_add_u32 s7, s7, s29
	s_mul_i32 s7, s7, 2048
	s_lshl_b32 s29, s8, 7
	s_add_u32 s7, s7, s29
	s_mul_i32 s29, s28, 4096
	s_add_u32 s7, s7, s29
	s_add_u32 s12, s26, 0x2100000
	s_addc_u32 s13, s27, 0
	s_add_u32 s12, s12, s7
	s_addc_u32 s13, s13, 0
	s_mov_b32 s14, 90112
	s_mov_b32 s15, 32768
	s_movk_i32 s16, 2048
	s_branch .Ltc6_segend_1

; __device__ __forceinline__ unsigned cvt_pk_bf16(float lo, float hi) { const f32x2_t v = {lo, hi}; const bf16x2_t b = __builtin_convertvector(v, bf16x2_t); return __builtin_bit_cast(unsigned, b); }
; __device__ __forceinline__ void tconv_list(const float* wg, const float* wu, const float* wd, const float* win, const float* wout, unsigned char* ws, const int ntiles, LAS float* t, const int wv) {
;     ...
; #pragma unroll
;         for (int e = 0; e < 8; ++e) { const int idx = e * 512 + tid, r = idx >> 6, c = idx & 63; t[r * 65 + c] = cur[e]; }
;         __syncthreads();
; #pragma unroll
;         for (int e = 0; e < 4; ++e) { const int idx = e * 512 + tid, n = idx >> 5, kp = idx & 31;
;             const unsigned w = pg8::cvt_pk_bf16(t[(2 * kp) * 65 + n], t[(2 * kp + 1) * 65 + n]);
;             *(unsigned*)(d.Bt + (size_t)(d.brow0 + n) * d.K + d.k0 + 2 * kp) = w; }
;         __syncthreads();
; #pragma unroll
;         for (int e = 0; e < 8; ++e) cur[e] = nxt[e];
.Ltc6_havea:
	ds_write_b32 v5, v8 offset:0
	ds_write_b32 v5, v9 offset:2080
	ds_write_b32 v5, v10 offset:4160
	ds_write_b32 v5, v11 offset:6240
	ds_write_b32 v5, v12 offset:8320
	ds_write_b32 v5, v13 offset:10400
	ds_write_b32 v5, v14 offset:12480
	ds_write_b32 v5, v15 offset:14560
	v_mad_u32_u24 v4, v2, s30, v3
	s_waitcnt lgkmcnt(0)
	s_barrier
	ds_read2_b32 v[24:25], v6 offset0:0 offset1:65
	ds_read2_b32 v[26:27], v6 offset0:16 offset1:81
	ds_read2_b32 v[28:29], v6 offset0:32 offset1:97
	ds_read2_b32 v[30:31], v6 offset0:48 offset1:113
	s_waitcnt lgkmcnt(3)
	v_cvt_pk_bf16_f32 v32, v24, v25
	s_waitcnt lgkmcnt(2)
	v_cvt_pk_bf16_f32 v33, v26, v27
	s_waitcnt lgkmcnt(1)
	v_cvt_pk_bf16_f32 v34, v28, v29
	s_waitcnt lgkmcnt(0)
	v_cvt_pk_bf16_f32 v35, v30, v31
	global_store_dword v4, v32, s[8:9]
	s_add_u32 s8, s8, s17
	s_addc_u32 s9, s9, 0
	global_store_dword v4, v33, s[8:9]
	s_add_u32 s8, s8, s17
	s_addc_u32 s9, s9, 0
	global_store_dword v4, v34, s[8:9]
	s_add_u32 s8, s8, s17
	s_addc_u32 s9, s9, 0
	global_store_dword v4, v35, s[8:9]
	s_barrier
	s_cmp_eq_u32 s31, 0
	s_cbranch_scc1 .Ltc6_done
	s_mov_b32 s17, s15
	s_mov_b32 s30, s16
	s_mov_b64 s[8:9], s[12:13]
	s_add_u32 s4, s4, 84
	s_cmp_lt_u32 s4, 840
	s_cselect_b32 s31, 1, 0
	s_cbranch_scc0 .Ltc6_nonextb
	v_writelane_b32 v40, s8, 32
	v_writelane_b32 v40, s9, 33
	s_cmp_lt_u32 s4, 704
	s_cbranch_scc0 .Ltc6_seg1_2
	s_mov_b32 s7, s4
	s_and_b32 s8, s7, 15
	s_lshr_b32 s9, s7, 4
	s_mul_i32 s7, s8, 720896
	s_lshl_b32 s29, s9, 8
	s_add_u32 s7, s7, s29
	s_mul_i32 s29, s28, 11264
	s_add_u32 s7, s7, s29
	s_add_u32 s10, s18, s7
	s_addc_u32 s11, s19, 0
	s_lshr_b32 s7, s9, 1
	s_lshl_b32 s7, s7, 8
	s_and_b32 s29, s9, 1
	s_lshl_b32 s29, s29, 6
	s_add_u32 s7, s7, s29
	s_mul_i32 s7, s7, 2048
	s_lshl_b32 s29, s8, 7
	s_add_u32 s7, s7, s29
	s_mul_i32 s29, s28, 4096
	s_add_u32 s7, s7, s29
	s_add_u32 s12, s26, 0x2100000
	s_addc_u32 s13, s27, 0
	s_add_u32 s12, s12, s7
	s_addc_u32 s13, s13, 0
	s_mov_b32 s14, 90112
	s_mov_b32 s15, 32768
	s_movk_i32 s16, 2048
	s_branch .Ltc6_segend_2

; __device__ __forceinline__ int fresh_tid(int wv) { int l; asm volatile("v_mbcnt_lo_u32_b32 %0, -1, 0\n\tv_mbcnt_hi_u32_b32 %0, -1, %0" : "=v"(l)); return wv * 64 + l; }
; #define LAS __attribute__((address_space(3)))
; __device__ __forceinline__ void tconv_list(const float* wg, const float* wu, const float* wd, const float* win, const float* wout, unsigned char* ws, const int ntiles, LAS float* t, const int wv) {
;     const int tid = fresh_tid(wv); const int G = gridDim.x;
;     float cur[8], nxt[8];
;     int i = blockIdx.x;
;     if (i < ntiles) { const TDesc d = tconv_desc(wg, wu, wd, win, wout, ws, i);
; #pragma unroll
;         for (int e = 0; e < 8; ++e) { const int idx = e * 512 + tid, r = idx >> 6, c = idx & 63; cur[e] = __builtin_nontemporal_load(d.W + (size_t)(d.k0 + r) * d.N + d.n0 + c); } }
.LBB0_847:
	s_cmp_lt_u32 s2, 32
	s_cbranch_scc1 .Ltc4_skip
	v_writelane_b32 v40, s4, 4
	v_writelane_b32 v40, s5, 5
	v_writelane_b32 v40, s6, 6
	v_writelane_b32 v40, s7, 7
	v_writelane_b32 v40, s8, 8
	v_writelane_b32 v40, s9, 9
	v_writelane_b32 v40, s10, 10
	v_writelane_b32 v40, s11, 11
	v_writelane_b32 v40, s12, 12
	v_writelane_b32 v40, s13, 13
	v_writelane_b32 v40, s14, 14
	v_writelane_b32 v40, s15, 15
	v_writelane_b32 v40, s16, 16
	v_writelane_b32 v40, s17, 17
	v_writelane_b32 v40, s18, 18
	v_writelane_b32 v40, s19, 19
	v_writelane_b32 v40, s20, 20
	v_writelane_b32 v40, s21, 21
	v_writelane_b32 v40, s22, 22
	v_writelane_b32 v40, s23, 23
	v_writelane_b32 v40, s24, 24
	v_writelane_b32 v40, s25, 25
	v_writelane_b32 v40, s26, 26
	v_writelane_b32 v40, s27, 27
	v_writelane_b32 v40, s28, 28
	v_writelane_b32 v40, s29, 29
	v_writelane_b32 v40, s30, 30
	v_writelane_b32 v40, s31, 31
	s_load_dwordx2 s[24:25], s[38:39], 0xd8
	s_load_dwordx2 s[26:27], s[38:39], 0xd0
	s_load_dwordx2 s[18:19], s[38:39], 0xb8
	s_load_dwordx2 s[20:21], s[38:39], 0xc0
	s_load_dwordx2 s[22:23], s[38:39], 0xc8
	v_mbcnt_lo_u32_b32 v0, -1, 0
	v_mbcnt_hi_u32_b32 v0, -1, v0
	s_lshr_b32 s28, s33, 6
	v_lshlrev_b32_e32 v1, 2, v0
	v_lshrrev_b32_e32 v2, 5, v0
	v_and_b32_e32 v3, 31, v0
	s_mul_i32 s7, s28, 260
	v_add_u32_e32 v5, s7, v1
	v_mul_u32_u24_e32 v6, 0x208, v3
	s_lshl_b32 s7, s28, 3
	v_lshl_add_u32 v6, v2, 2, v6
	v_add_u32_e32 v6, s7, v6
	v_lshlrev_b32_e32 v3, 2, v3
	s_sub_u32 s4, s2, 32
	s_add_u32 s4, s4, 840
	s_waitcnt lgkmcnt(0)
	s_cmp_lt_u32 s4, 704
	s_cbranch_scc0 .Ltc4_seg1_0
	s_mov_b32 s7, s4
	s_and_b32 s8, s7, 15
	s_lshr_b32 s9, s7, 4
	s_mul_i32 s7, s8, 720896
	s_lshl_b32 s29, s9, 8
	s_add_u32 s7, s7, s29
	s_mul_i32 s29, s28, 11264
	s_add_u32 s7, s7, s29
	s_add_u32 s10, s18, s7
	s_addc_u32 s11, s19, 0
	s_lshr_b32 s7, s9, 1
	s_lshl_b32 s7, s7, 8
	s_and_b32 s29, s9, 1
	s_lshl_b32 s29, s29, 6
	s_add_u32 s7, s7, s29
	s_mul_i32 s7, s7, 2048
	s_lshl_b32 s29, s8, 7
	s_add_u32 s7, s7, s29
	s_mul_i32 s29, s28, 4096
	s_add_u32 s7, s7, s29
	s_add_u32 s12, s26, 0x2100000
	s_addc_u32 s13, s27, 0
	s_add_u32 s12, s12, s7
	s_addc_u32 s13, s13, 0
	s_mov_b32 s14, 90112
	s_mov_b32 s15, 32768
	s_movk_i32 s16, 2048
	s_branch .Ltc4_segend_0
